# prologue x->fp16 stream conversion: four loads in flight per row instead of load-wait-convert-store serial chain
# speedup vs baseline: 1.0052x; 1.0002x over previous
; __device__ __forceinline__ unsigned pkh(float lo, float hi) { f32x2p v = {lo, hi}; return __builtin_bit_cast(unsigned, __builtin_convertvector(v, h16x2)); }
; __device__ __forceinline__ void prologue(CArgsP ap_, LAS unsigned char* lds, int gw, int ngw, int wave, int lane) {
;     ...
;     for (int row = gw; row < MTOT; row += ngw) {
;         const float* src = row < MHALF ? a.in[0] + (size_t)row * DM : a.in[1] + (size_t)(row - MHALF) * DM;
;         const f32x4* xr = (const f32x4*)src + lane; v2u* ob = (v2u*)(XB + (size_t)row * DM) + lane;
; #pragma unroll
;         for (int j = 0; j < 4; ++j) { const f32x4 v = xr[64 * j]; v2u w; w.x = pkh(v[0], v[1]); w.y = pkh(v[2], v[3]); ob[64 * j] = w; }
;     }
.LBB0_50:
	global_load_dwordx4 v[6:9], v1, s[24:25]
	global_load_dwordx4 v[80:83], v1, s[24:25] offset:1024
	global_load_dwordx4 v[84:87], v1, s[24:25] offset:2048
	global_load_dwordx4 v[88:91], v1, s[24:25] offset:3072
	s_lshl_b64 s[26:27], s[26:27], 11
	v_lshl_add_u64 v[10:11], v[4:5], 0, s[26:27]
	s_add_u32 s14, s14, s22
	s_addc_u32 s15, s15, s23
	s_add_u32 s4, s4, s6
	s_addc_u32 s5, s5, s7
	s_cmp_gt_i32 s14, 0xffff
	s_waitcnt vmcnt(3)
	v_cvt_pk_f16_f32 v6, v6, v7
	v_cvt_pk_f16_f32 v7, v8, v9
	s_waitcnt vmcnt(2)
	v_cvt_pk_f16_f32 v80, v80, v81
	v_cvt_pk_f16_f32 v81, v82, v83
	s_waitcnt vmcnt(1)
	v_cvt_pk_f16_f32 v84, v84, v85
	v_cvt_pk_f16_f32 v85, v86, v87
	s_waitcnt vmcnt(0)
	v_cvt_pk_f16_f32 v88, v88, v89
	v_cvt_pk_f16_f32 v89, v90, v91
	global_store_dwordx2 v[10:11], v[6:7], off
	global_store_dwordx2 v[10:11], v[80:81], off offset:512
	global_store_dwordx2 v[10:11], v[84:85], off offset:1024
	global_store_dwordx2 v[10:11], v[88:89], off offset:1536
	s_cbranch_scc1 .LBB0_53
